# NA attention tile loop: bias add on the score tile done with 14 scalar adds in place instead of the compiler's shift-by-one register shuffle (28 v_mov + 4 pk_mov + 7 pk_add)
# speedup vs baseline: 1.0095x; 1.0038x over previous
; #define LAS __attribute__((address_space(3)))
; template <int KIND> ...
;     ...
;                 s16x4 vfa[2][NDT][2], vfb[2][NDT][2];
; #pragma unroll
;                 for (int s = 0; s < 2; ++s)
; #pragma unroll
;                     for (int dt = 0; dt < NDT; ++dt) {
;                         vfa[s][dt][0] = __builtin_amdgcn_ds_read_tr16_b64_v4i16((LAS s16x4*)(lds + buf * VBUF + voff + (16 * s) * VSTR + 64 * dt));
;                         vfa[s][dt][1] = __builtin_amdgcn_ds_read_tr16_b64_v4i16((LAS s16x4*)(lds + buf * VBUF + voff + (16 * s + 8) * VSTR + 64 * dt)); }
;                 __builtin_amdgcn_sched_barrier(0);
;                 if (na_lat) {
; #pragma unroll
;                     for (int j = 0; j < 16; ++j) { s0[j] += ab0[j]; s1[j] += ab1[j]; }
;                 }
.LBB0_150:
	s_mulk_i32 s83, 0x3000
	v_add_u32_e32 v238, s83, v213
	ds_read_b64_tr_b16 v[148:149], v238 offset:18432
	ds_read_b64_tr_b16 v[150:151], v238 offset:19968
	ds_read_b64_tr_b16 v[146:147], v238 offset:20032
	ds_read_b64_tr_b16 v[144:145], v238 offset:18496
	ds_read_b64_tr_b16 v[140:141], v238 offset:21504
	ds_read_b64_tr_b16 v[142:143], v238 offset:23040
	ds_read_b64_tr_b16 v[138:139], v238 offset:23104
	ds_read_b64_tr_b16 v[136:137], v238 offset:21568
	s_and_b64 vcc, exec, s[78:79]
	s_cbranch_vccz .LBB0_152
	v_add_f32_e32 v65, v65, v160
	v_add_f32_e32 v66, v66, v166
	v_add_f32_e32 v67, v67, v167
	v_add_f32_e32 v68, v68, v168
	v_add_f32_e32 v69, v69, v169
	v_add_f32_e32 v70, v70, v172
	v_add_f32_e32 v71, v71, v173
	v_add_f32_e32 v72, v72, v177
	v_add_f32_e32 v73, v73, v178
	v_add_f32_e32 v74, v74, v180
	v_add_f32_e32 v75, v75, v181
	v_add_f32_e32 v76, v76, v186
	v_add_f32_e32 v77, v77, v187
	v_add_f32_e32 v78, v78, v190
	v_add_f32_e32 v206, v64, v236
	v_pk_add_f32 v[80:81], v[96:97], v[162:163]
	v_pk_add_f32 v[94:95], v[110:111], v[200:201]
	v_pk_add_f32 v[92:93], v[108:109], v[188:189]
	v_pk_add_f32 v[90:91], v[106:107], v[184:185]
	v_pk_add_f32 v[88:89], v[104:105], v[182:183]
	v_pk_add_f32 v[86:87], v[102:103], v[174:175]
	v_pk_add_f32 v[84:85], v[100:101], v[170:171]
	v_pk_add_f32 v[82:83], v[98:99], v[164:165]
	v_add_f32_e32 v161, v79, v191
	s_cbranch_execz .LBB0_153
	s_branch .LBB0_154
